# attention steady loop: next STEP's G-table quads prefetched into free VGPRs right after the current subs (no LDS wait after the barrier), on top of v10
# speedup vs baseline: 1.0028x; 1.0026x over previous
.LBB0_1339:
	v_lshlrev_b32_e32 v0, 1, v46
	v_and_b32_e32 v211, 32, v0
	v_and_b32_e32 v0, 0xc0, v2
	v_lshl_or_b32 v210, v207, 8, v0
	v_add_u32_e32 v0, 0, v211
	v_add3_u32 v216, v0, v208, v210
	v_max3_f32 v0, v4, v5, v20
	v_max3_f32 v1, v6, v7, v21
	s_and_b32 s4, s20, 0x3fffffc0
	v_max3_f32 v0, v0, v22, v23
	v_max3_f32 v1, v1, v10, v11
	s_lshl_b32 s4, s4, 2
	v_max3_f32 v0, v0, v8, v9
	v_max3_f32 v1, v1, v26, v27
	s_waitcnt vmcnt(0) lgkmcnt(0)
	s_barrier
	s_add_i32 s20, s4, 0
	v_max3_f32 v0, v0, v24, v25
	v_max3_f32 v1, v1, v14, v15
	s_cmp_lg_u32 0, -1
	v_max3_f32 v0, v0, v12, v13
	v_max3_f32 v1, v1, v30, v31
	s_mov_b32 s9, 1
	v_max3_f32 v0, v0, v28, v29
	v_max3_f32 v1, v1, v18, v19
	s_mov_b32 s14, 0
	v_max3_f32 v0, v0, v16, v17
	v_max3_f32 v1, v1, v34, v35
	v_cmp_gt_u32_e64 s[40:41], 32, v204
	v_max3_f32 v0, v0, v32, v33
	v_lshl_add_u32 v213, v206, 2, s20
	v_max_f32_e32 v0, v0, v1
	s_nop 0
	v_mov_b32_e32 v1, v0
	s_nop 1
	v_permlane32_swap_b32_e32 v0, v1
	v_max_f32_e32 v0, v0, v1
	s_nop 0
	v_add_f32_e32 v217, v3, v0
	v_sub_f32_e32 v1, v4, v0
	v_sub_f32_e32 v2, v20, v0
	v_sub_f32_e32 v4, v5, v0
	v_sub_f32_e32 v5, v21, v0
	v_sub_f32_e32 v6, v6, v0
	v_sub_f32_e32 v20, v22, v0
	v_sub_f32_e32 v7, v7, v0
	v_sub_f32_e32 v21, v23, v0
	v_sub_f32_e32 v8, v8, v0
	v_sub_f32_e32 v22, v24, v0
	v_sub_f32_e32 v9, v9, v0
	v_sub_f32_e32 v23, v25, v0
	v_sub_f32_e32 v10, v10, v0
	v_sub_f32_e32 v24, v26, v0
	v_sub_f32_e32 v11, v11, v0
	v_sub_f32_e32 v25, v27, v0
	v_sub_f32_e32 v12, v12, v0
	v_sub_f32_e32 v26, v28, v0
	v_sub_f32_e32 v13, v13, v0
	v_sub_f32_e32 v27, v29, v0
	v_sub_f32_e32 v14, v14, v0
	v_sub_f32_e32 v28, v30, v0
	v_sub_f32_e32 v15, v15, v0
	v_sub_f32_e32 v29, v31, v0
	v_sub_f32_e32 v16, v16, v0
	v_sub_f32_e32 v30, v32, v0
	v_sub_f32_e32 v17, v17, v0
	v_sub_f32_e32 v31, v33, v0
	v_sub_f32_e32 v18, v18, v0
	v_sub_f32_e32 v32, v34, v0
	v_sub_f32_e32 v19, v19, v0
	v_sub_f32_e32 v0, v35, v0
	s_nop 0
	v_exp_f32_e32 v64, v1
	v_exp_f32_e32 v63, v0
	v_lshl_add_u64 v[0:1], v[200:201], 0, s[60:61]
	s_mov_b32 s4, m0
	s_mov_b32 m0, s21
	s_nop 0
	global_load_lds_dwordx4 v[0:1], off
	s_mov_b32 m0, s4
	s_mov_b64 s[4:5], 0x20000
	v_lshl_add_u64 v[0:1], v[202:203], 0, s[4:5]
	s_cselect_b32 s4, 0, 0
	s_add_i32 s0, s4, s0
	s_add_i32 s0, s0, 0x8000
	s_mov_b32 s4, m0
	s_mov_b32 m0, s0
	s_nop 0
	global_load_lds_dwordx4 v[0:1], off
	s_mov_b32 m0, s4
	ds_read_b128 v[172:175], v215 offset:8192
	ds_read_b128 v[168:171], v215 offset:8704
	ds_read_b128 v[164:167], v215 offset:10240
	ds_read_b128 v[160:163], v215 offset:10752
	ds_read_b128 v[156:159], v215 offset:12288
	ds_read_b128 v[152:155], v215 offset:12800
	ds_read_b128 v[148:151], v215 offset:14336
	ds_read_b128 v[144:147], v215 offset:14848
	v_exp_f32_e32 v65, v4
	v_exp_f32_e32 v66, v6
	v_exp_f32_e32 v67, v7
	v_exp_f32_e32 v68, v8
	v_exp_f32_e32 v69, v9
	v_exp_f32_e32 v70, v10
	v_exp_f32_e32 v71, v11
	v_exp_f32_e32 v72, v12
	v_exp_f32_e32 v73, v13
	v_exp_f32_e32 v74, v14
	v_exp_f32_e32 v75, v15
	v_exp_f32_e32 v76, v16
	v_exp_f32_e32 v77, v17
	v_exp_f32_e32 v78, v18
	v_exp_f32_e32 v79, v19
	v_exp_f32_e32 v48, v2
	v_exp_f32_e32 v49, v5
	v_exp_f32_e32 v50, v20
	v_exp_f32_e32 v51, v21
	v_exp_f32_e32 v52, v22
	v_exp_f32_e32 v53, v23
	v_exp_f32_e32 v54, v24
	v_exp_f32_e32 v55, v25
	v_exp_f32_e32 v56, v26
	v_exp_f32_e32 v57, v27
	v_exp_f32_e32 v58, v28
	v_exp_f32_e32 v59, v29
	v_exp_f32_e32 v60, v30
	v_exp_f32_e32 v61, v31
	v_exp_f32_e32 v62, v32
	s_waitcnt vmcnt(2) lgkmcnt(0)
	s_barrier
	s_cmp_lt_i32 s24, 7
	s_cbranch_scc1 .LBB0_1355
	v_mov_b32_e32 v14, v3
	v_mov_b32_e32 v15, v3
	s_mov_b64 s[4:5], 0xa0000
	s_add_i32 s8, s8, 0x14900
	v_mov_b32_e32 v0, v3
	v_mov_b32_e32 v1, v3
	v_mov_b32_e32 v2, v3
	v_mov_b32_e32 v4, v3
	v_mov_b32_e32 v5, v3
	v_mov_b32_e32 v6, v3
	v_mov_b32_e32 v7, v3
	v_mov_b32_e32 v8, v3
	v_mov_b32_e32 v9, v3
	v_mov_b32_e32 v10, v3
	v_mov_b32_e32 v11, v3
	v_mov_b32_e32 v12, v3
	v_mov_b32_e32 v13, v3
	v_mov_b64_e32 v[46:47], v[14:15]
	v_mov_b64_e32 v[30:31], v[14:15]
	v_lshl_add_u64 v[176:177], v[202:203], 0, s[60:61]
	v_lshl_add_u64 v[178:179], v[200:201], 0, s[4:5]
	v_add_u32_e32 v180, s8, v209
	s_mov_b32 s8, 0
	s_movk_i32 s14, 0x4000
	s_movk_i32 s16, 0x2000
	v_mov_b32_e32 v218, 0
	s_mov_b32 s15, 6
	v_mov_b64_e32 v[44:45], v[12:13]
	v_mov_b64_e32 v[42:43], v[10:11]
	v_mov_b64_e32 v[40:41], v[8:9]
	v_mov_b64_e32 v[38:39], v[6:7]
	v_mov_b64_e32 v[36:37], v[4:5]
	v_mov_b64_e32 v[34:35], v[2:3]
	v_mov_b64_e32 v[32:33], v[0:1]
	v_mov_b64_e32 v[28:29], v[12:13]
	v_mov_b64_e32 v[26:27], v[10:11]
	v_mov_b64_e32 v[24:25], v[8:9]
	v_mov_b64_e32 v[22:23], v[6:7]
	v_mov_b64_e32 v[20:21], v[4:5]
	v_mov_b64_e32 v[18:19], v[2:3]
	v_mov_b64_e32 v[16:17], v[0:1]
	ds_read_b128 v[188:191], v180
	ds_read_b128 v[192:195], v180 offset:32
	ds_read_b128 v[196:199], v180 offset:64
	ds_read_b128 v[220:223], v180 offset:96
	ds_read_b128 v[224:227], v180 offset:128
	ds_read_b128 v[228:231], v180 offset:160
	ds_read_b128 v[232:235], v180 offset:192
	ds_read_b128 v[236:239], v180 offset:224
.LBB0_1341:
	v_sub_f32_e32 v0, v214, v217
	s_waitcnt lgkmcnt(4)
	v_sub_f32_e32 v111, v0, v223
	v_sub_f32_e32 v110, v0, v222
	v_sub_f32_e32 v109, v0, v221
	v_sub_f32_e32 v108, v0, v220
	v_sub_f32_e32 v107, v0, v199
	v_sub_f32_e32 v106, v0, v198
	v_sub_f32_e32 v105, v0, v197
	v_sub_f32_e32 v104, v0, v196
	v_sub_f32_e32 v103, v0, v195
	v_sub_f32_e32 v102, v0, v194
	v_sub_f32_e32 v101, v0, v193
	v_sub_f32_e32 v100, v0, v192
	v_sub_f32_e32 v99, v0, v191
	v_sub_f32_e32 v98, v0, v190
	v_sub_f32_e32 v97, v0, v189
	v_sub_f32_e32 v96, v0, v188
	s_waitcnt lgkmcnt(0)
	v_sub_f32_e32 v95, v0, v239
	v_sub_f32_e32 v94, v0, v238
	v_sub_f32_e32 v93, v0, v237
	v_sub_f32_e32 v92, v0, v236
	v_sub_f32_e32 v91, v0, v235
	v_sub_f32_e32 v90, v0, v234
	v_sub_f32_e32 v89, v0, v233
	v_sub_f32_e32 v88, v0, v232
	v_sub_f32_e32 v87, v0, v231
	v_sub_f32_e32 v86, v0, v230
	v_sub_f32_e32 v85, v0, v229
	v_sub_f32_e32 v84, v0, v228
	v_sub_f32_e32 v83, v0, v227
	v_sub_f32_e32 v82, v0, v226
	v_sub_f32_e32 v81, v0, v225
	v_sub_f32_e32 v80, v0, v224
	ds_read_b128 v[188:191], v180 offset:256
	ds_read_b128 v[192:195], v180 offset:288
	ds_read_b128 v[196:199], v180 offset:320
	ds_read_b128 v[220:223], v180 offset:352
	ds_read_b128 v[224:227], v180 offset:384
	ds_read_b128 v[228:231], v180 offset:416
	ds_read_b128 v[232:235], v180 offset:448
	ds_read_b128 v[236:239], v180 offset:480
	v_add_u32_e32 v0, s8, v216
	ds_read_b64_tr_b16 v[4:5], v0 offset:24576
	ds_read_b64_tr_b16 v[6:7], v0 offset:25088
	v_mfma_f32_32x32x16_bf16 v[96:111], v[172:175], v[124:127], v[96:111]
	v_add_f32_e32 v1, v64, v65
	v_add_f32_e32 v1, v66, v1
	v_add_f32_e32 v1, v67, v1
	v_add_f32_e32 v1, v68, v1
	v_add_f32_e32 v1, v69, v1
	v_cvt_pk_bf16_f32 v140, v64, v65
	v_cvt_pk_bf16_f32 v141, v66, v67
	ds_read_b64_tr_b16 v[8:9], v0 offset:28672
	ds_read_b64_tr_b16 v[10:11], v0 offset:29184
	v_mfma_f32_32x32x16_bf16 v[80:95], v[168:171], v[124:127], v[80:95]
	v_add_f32_e32 v1, v70, v1
	v_add_f32_e32 v1, v71, v1
	v_add_f32_e32 v1, v72, v1
	v_add_f32_e32 v1, v73, v1
	v_cvt_pk_bf16_f32 v142, v68, v69
	v_cvt_pk_bf16_f32 v143, v70, v71
	ds_read_b64_tr_b16 v[12:13], v0 offset:25600
	ds_read_b64_tr_b16 v[14:15], v0 offset:26112
	v_mfma_f32_32x32x16_bf16 v[96:111], v[164:167], v[120:123], v[96:111]
	v_add_f32_e32 v1, v74, v1
	v_add_f32_e32 v1, v75, v1
	v_add_f32_e32 v1, v76, v1
	v_add_f32_e32 v1, v77, v1
	v_cvt_pk_bf16_f32 v136, v72, v73
	v_cvt_pk_bf16_f32 v137, v74, v75
	ds_read_b64_tr_b16 v[64:65], v0 offset:29696
	ds_read_b64_tr_b16 v[66:67], v0 offset:30208
	v_mfma_f32_32x32x16_bf16 v[80:95], v[160:163], v[120:123], v[80:95]
	v_add_f32_e32 v1, v78, v1
	v_add_f32_e32 v1, v79, v1
	v_add_f32_e32 v1, v48, v1
	v_add_f32_e32 v1, v49, v1
	v_cvt_pk_bf16_f32 v138, v76, v77
	v_cvt_pk_bf16_f32 v139, v78, v79
	ds_read_b64_tr_b16 v[68:69], v0 offset:26624
	ds_read_b64_tr_b16 v[70:71], v0 offset:27136
	v_mfma_f32_32x32x16_bf16 v[96:111], v[156:159], v[116:119], v[96:111]
	v_add_f32_e32 v1, v50, v1
	v_add_f32_e32 v1, v51, v1
	v_add_f32_e32 v1, v52, v1
	v_add_f32_e32 v1, v53, v1
	v_cvt_pk_bf16_f32 v132, v48, v49
	v_cvt_pk_bf16_f32 v133, v50, v51
	ds_read_b64_tr_b16 v[48:49], v0 offset:30720
	ds_read_b64_tr_b16 v[50:51], v0 offset:31232
	v_mfma_f32_32x32x16_bf16 v[80:95], v[152:155], v[116:119], v[80:95]
	v_add_f32_e32 v1, v54, v1
	v_add_f32_e32 v1, v55, v1
	v_add_f32_e32 v1, v56, v1
	v_add_f32_e32 v1, v57, v1
	v_cvt_pk_bf16_f32 v134, v52, v53
	v_cvt_pk_bf16_f32 v135, v54, v55
	ds_read_b64_tr_b16 v[52:53], v0 offset:27648
	ds_read_b64_tr_b16 v[54:55], v0 offset:28160
	v_mfma_f32_32x32x16_bf16 v[96:111], v[148:151], v[112:115], v[96:111]
	v_add_f32_e32 v1, v58, v1
	v_add_f32_e32 v1, v59, v1
	v_add_f32_e32 v1, v60, v1
	v_add_f32_e32 v1, v61, v1
	v_cvt_pk_bf16_f32 v128, v56, v57
	v_cvt_pk_bf16_f32 v129, v58, v59
	ds_read_b64_tr_b16 v[56:57], v0 offset:31744
	ds_read_b64_tr_b16 v[58:59], v0 offset:32256
	v_mfma_f32_32x32x16_bf16 v[80:95], v[144:147], v[112:115], v[80:95]
	v_add_f32_e32 v0, v62, v1
	v_add_f32_e32 v0, v63, v0
	v_add_f32_e32 v2, 0, v0
	v_cvt_pk_bf16_f32 v130, v60, v61
	v_cvt_pk_bf16_f32 v131, v62, v63
	s_mov_b32 s8, 0xfffe0000
	s_mov_b32 s9, -1
	v_lshl_add_u64 v[0:1], v[178:179], 0, s[8:9]
	s_add_i32 s0, s16, s21
	s_mov_b32 s4, m0
	s_mov_b32 m0, s0
	s_nop 0
	global_load_lds_dwordx4 v[0:1], off
	s_mov_b32 m0, s4
	v_lshl_add_u64 v[0:1], v[176:177], 0, s[8:9]
	s_add_i32 s0, s14, s22
	s_mov_b32 s4, m0
	s_mov_b32 m0, s0
	s_nop 0
	global_load_lds_dwordx4 v[0:1], off
	s_mov_b32 m0, s4
	v_max_f32_e32 v0, v97, v97
	v_max_f32_e32 v1, v96, v96
	v_max_f32_e32 v0, v1, v0
	v_max3_f32 v1, v98, v99, v81
	v_max3_f32 v0, v0, v80, v82
	v_max3_f32 v0, v0, v83, v100
	v_max3_f32 v1, v1, v102, v103
	v_max3_f32 v0, v0, v101, v84
	v_max3_f32 v1, v1, v86, v87
	v_max3_f32 v0, v0, v85, v104
	v_max3_f32 v1, v1, v106, v107
	v_max3_f32 v0, v0, v105, v88
	v_max3_f32 v1, v1, v90, v91
	v_max3_f32 v0, v0, v89, v108
	v_max3_f32 v1, v1, v110, v111
	v_max3_f32 v60, v0, v109, v92
	v_max3_f32 v1, v1, v94, v95
	v_max3_f32 v1, v60, v93, v1
	v_add_f32_e32 v0, v218, v2
	v_mov_b32_e32 v2, v1
	s_nop 1
	v_permlane32_swap_b32_e32 v1, v2
	v_max_f32_e32 v2, v2, v2
	v_max_f32_e32 v1, v1, v1
	v_max_f32_e32 v1, v1, v2
	v_cmp_lt_f32_e32 vcc, s33, v1
	s_cmp_lg_u64 vcc, 0
	s_cselect_b64 s[8:9], -1, 0
	s_cbranch_vccnz .LBB0_1349

.LBB0_1344:
	s_add_i32 s0, s14, 0x2000
	s_cmpk_lg_i32 s14, 0x4000
	s_cselect_b32 s25, s0, 0
	v_sub_f32_e32 v1, v214, v217
	s_waitcnt lgkmcnt(4)
	v_sub_f32_e32 v79, v1, v223
	v_sub_f32_e32 v78, v1, v222
	v_sub_f32_e32 v77, v1, v221
	v_sub_f32_e32 v76, v1, v220
	v_sub_f32_e32 v75, v1, v199
	v_sub_f32_e32 v74, v1, v198
	v_sub_f32_e32 v73, v1, v197
	v_sub_f32_e32 v72, v1, v196
	v_sub_f32_e32 v71, v1, v195
	v_sub_f32_e32 v70, v1, v194
	v_sub_f32_e32 v69, v1, v193
	v_sub_f32_e32 v68, v1, v192
	v_sub_f32_e32 v67, v1, v191
	v_sub_f32_e32 v66, v1, v190
	v_sub_f32_e32 v65, v1, v189
	v_sub_f32_e32 v64, v1, v188
	s_waitcnt lgkmcnt(0)
	v_sub_f32_e32 v63, v1, v239
	v_sub_f32_e32 v62, v1, v238
	v_sub_f32_e32 v61, v1, v237
	v_sub_f32_e32 v60, v1, v236
	v_sub_f32_e32 v59, v1, v235
	v_sub_f32_e32 v58, v1, v234
	v_sub_f32_e32 v57, v1, v233
	v_sub_f32_e32 v56, v1, v232
	v_sub_f32_e32 v55, v1, v231
	v_sub_f32_e32 v54, v1, v230
	v_sub_f32_e32 v53, v1, v229
	v_sub_f32_e32 v52, v1, v228
	v_sub_f32_e32 v51, v1, v227
	v_sub_f32_e32 v50, v1, v226
	v_sub_f32_e32 v49, v1, v225
	v_sub_f32_e32 v48, v1, v224
	ds_read_b128 v[188:191], v180 offset:512
	ds_read_b128 v[192:195], v180 offset:544
	ds_read_b128 v[196:199], v180 offset:576
	ds_read_b128 v[220:223], v180 offset:608
	ds_read_b128 v[224:227], v180 offset:640
	ds_read_b128 v[228:231], v180 offset:672
	ds_read_b128 v[232:235], v180 offset:704
	ds_read_b128 v[236:239], v180 offset:736
	v_add_u32_e32 v1, s16, v216
	ds_read_b64_tr_b16 v[152:153], v1 offset:24576
	ds_read_b64_tr_b16 v[154:155], v1 offset:25088
	v_mfma_f32_32x32x16_bf16 v[64:79], v[164:167], v[124:127], v[64:79]
	v_add_f32_e32 v2, v96, v97
	v_add_f32_e32 v2, v98, v2
	v_add_f32_e32 v2, v99, v2
	v_add_f32_e32 v2, v100, v2
	v_add_f32_e32 v2, v101, v2
	v_cvt_pk_bf16_f32 v140, v96, v97
	v_cvt_pk_bf16_f32 v141, v98, v99
	ds_read_b64_tr_b16 v[96:97], v1 offset:28672
	ds_read_b64_tr_b16 v[98:99], v1 offset:29184
	v_mfma_f32_32x32x16_bf16 v[48:63], v[160:163], v[124:127], v[48:63]
	v_add_f32_e32 v2, v102, v2
	v_add_f32_e32 v2, v103, v2
	v_add_f32_e32 v2, v104, v2
	v_add_f32_e32 v2, v105, v2
	v_cvt_pk_bf16_f32 v142, v100, v101
	v_cvt_pk_bf16_f32 v143, v102, v103
	ds_read_b64_tr_b16 v[100:101], v1 offset:25600
	ds_read_b64_tr_b16 v[102:103], v1 offset:26112
	v_mfma_f32_32x32x16_bf16 v[64:79], v[156:159], v[120:123], v[64:79]
	v_add_f32_e32 v2, v106, v2
	v_add_f32_e32 v2, v107, v2
	v_add_f32_e32 v2, v108, v2
	v_add_f32_e32 v2, v109, v2
	v_cvt_pk_bf16_f32 v136, v104, v105
	v_cvt_pk_bf16_f32 v137, v106, v107
	ds_read_b64_tr_b16 v[104:105], v1 offset:29696
	ds_read_b64_tr_b16 v[106:107], v1 offset:30208
	v_mfma_f32_32x32x16_bf16 v[48:63], v[148:151], v[120:123], v[48:63]
	v_add_f32_e32 v2, v110, v2
	v_add_f32_e32 v2, v111, v2
	v_add_f32_e32 v2, v80, v2
	v_add_f32_e32 v2, v81, v2
	v_cvt_pk_bf16_f32 v138, v108, v109
	v_cvt_pk_bf16_f32 v139, v110, v111
	ds_read_b64_tr_b16 v[108:109], v1 offset:26624
	ds_read_b64_tr_b16 v[110:111], v1 offset:27136
	v_mfma_f32_32x32x16_bf16 v[64:79], v[144:147], v[116:119], v[64:79]
	v_add_f32_e32 v2, v82, v2
	v_add_f32_e32 v2, v83, v2
	v_add_f32_e32 v2, v84, v2
	v_add_f32_e32 v2, v85, v2
	v_cvt_pk_bf16_f32 v132, v80, v81
	v_cvt_pk_bf16_f32 v133, v82, v83
	ds_read_b64_tr_b16 v[80:81], v1 offset:30720
	ds_read_b64_tr_b16 v[82:83], v1 offset:31232
	v_mfma_f32_32x32x16_bf16 v[48:63], v[12:15], v[116:119], v[48:63]
	v_add_f32_e32 v2, v86, v2
	v_add_f32_e32 v2, v87, v2
	v_add_f32_e32 v2, v88, v2
	v_add_f32_e32 v2, v89, v2
	v_cvt_pk_bf16_f32 v134, v84, v85
	v_cvt_pk_bf16_f32 v135, v86, v87
	ds_read_b64_tr_b16 v[12:13], v1 offset:27648
	ds_read_b64_tr_b16 v[14:15], v1 offset:28160
	v_mfma_f32_32x32x16_bf16 v[64:79], v[8:11], v[112:115], v[64:79]
	v_add_f32_e32 v2, v90, v2
	v_add_f32_e32 v2, v91, v2
	v_add_f32_e32 v2, v92, v2
	v_add_f32_e32 v2, v93, v2
	v_cvt_pk_bf16_f32 v128, v88, v89
	v_cvt_pk_bf16_f32 v129, v90, v91
	ds_read_b64_tr_b16 v[8:9], v1 offset:31744
	ds_read_b64_tr_b16 v[10:11], v1 offset:32256
	v_mfma_f32_32x32x16_bf16 v[48:63], v[4:7], v[112:115], v[48:63]
	v_add_f32_e32 v1, v94, v2
	v_add_f32_e32 v1, v95, v1
	v_add_f32_e32 v1, 0, v1
	v_cvt_pk_bf16_f32 v130, v92, v93
	v_cvt_pk_bf16_f32 v131, v94, v95
	v_max_f32_e32 v2, v65, v65
	v_max_f32_e32 v4, v64, v64
	v_max_f32_e32 v2, v4, v2
	s_nop 3
	v_max3_f32 v4, v66, v67, v49
	v_max3_f32 v2, v2, v48, v50
	v_max3_f32 v2, v2, v51, v68
	v_max3_f32 v4, v4, v70, v71
	v_max3_f32 v2, v2, v69, v52
	v_max3_f32 v4, v4, v54, v55
	v_max3_f32 v2, v2, v53, v72
	v_max3_f32 v4, v4, v74, v75
	v_max3_f32 v2, v2, v73, v56
	v_max3_f32 v4, v4, v58, v59
	v_max3_f32 v2, v2, v57, v76
	v_max3_f32 v4, v4, v78, v79
	v_max3_f32 v2, v2, v77, v60
	v_max3_f32 v4, v4, v62, v63
	v_add_f32_e32 v218, v0, v1
	v_max3_f32 v0, v2, v61, v4
	v_mov_b32_e32 v1, v0
	s_nop 1
	v_permlane32_swap_b32_e32 v0, v1
	v_max_f32_e32 v1, v1, v1
	v_max_f32_e32 v0, v0, v0
	s_add_i32 s0, s14, s21
	s_mov_b32 s4, m0
	s_mov_b32 m0, s0
	s_nop 0
	global_load_lds_dwordx4 v[178:179], off
	s_mov_b32 m0, s4
	v_max_f32_e32 v0, v0, v1
	s_add_i32 s0, s25, s22
	s_mov_b32 s4, m0
	s_mov_b32 m0, s0
	s_nop 0
	global_load_lds_dwordx4 v[176:177], off
	s_mov_b32 m0, s4
	v_cmp_lt_f32_e32 vcc, s33, v0
	s_cmp_lg_u64 vcc, 0
	s_cselect_b64 s[8:9], -1, 0
	s_cbranch_vccnz .LBB0_1352
